# select: unmasked copy of the chunk-0 key conversion for two-chunk items (all keys admissible)
# baseline (speedup 1.0000x reference)
; #define LAS __attribute__((address_space(3)))
; __device__ __forceinline__ void select_phase(const bf16_t* Z, const bf16_t* KIb, unsigned* MASKb, unsigned* itemcnt, LAS unsigned char* lds, int wave_in, int lane_in, int bid, int G, int sub) {
;     ...
;                 const LAS float* srow = sc + (2 * wave) * SCS + 36 * lane;
;                 const int ema = qa - 2048 * c - 32 * lane, emb = ema + 1;
;                 const int adma = (int)(ema >= 31 ? 0xffffffffu : ema < 0 ? 0u : ((2u << ema) - 1u)), admb = (int)(emb >= 31 ? 0xffffffffu : emb < 0 ? 0u : ((2u << emb) - 1u));
; #pragma unroll
;                 for (int e4 = 0; e4 < 8; ++e4) {
;                     const f32x4 va = *(const LAS f32x4*)(srow + 4 * e4), vb = *(const LAS f32x4*)(srow + SCS + 4 * e4);
; #pragma unroll
;                     for (int e = 0; e < 4; ++e) {
;                         const int ii = c * 32 + e4 * 4 + e;
;                         const unsigned ba = __float_as_uint(va[e]), bb = __float_as_uint(vb[e]);
;                         ua[ii] = (ba ^ ((unsigned)((int)ba >> 31) | 0x80000000u)) & (unsigned)__builtin_amdgcn_sbfe(adma, e4 * 4 + e, 1);
;                         ub[ii] = (bb ^ ((unsigned)((int)bb >> 31) | 0x80000000u)) & (unsigned)__builtin_amdgcn_sbfe(admb, e4 * 4 + e, 1);
;                         vmaxa = max(vmaxa, ua[ii]); vmaxb = max(vmaxb, ub[ii]);
;                     }
;                 }
.LBB0_123:
	s_cmp_lt_i32 s10, 2
	s_cbranch_scc0 .Lcv_fast
	v_sub_u32_e32 v34, s75, v172
	v_lshlrev_b32_e64 v35, v34, 2
	v_cmp_gt_i32_e32 vcc, 0, v34
	v_add_u32_e32 v35, -1, v35
	v_cmp_gt_i32_e64 s[4:5], 31, v34
	v_cndmask_b32_e64 v35, v35, 0, vcc
	v_add_u32_e32 v48, s9, v0
	v_cndmask_b32_e64 v46, -1, v35, s[4:5]
	v_lshlrev_b32_e64 v35, v34, 4
	v_add_u32_e32 v35, -1, v35
	v_cndmask_b32_e64 v35, v35, 0, vcc
	v_cmp_gt_i32_e32 vcc, 30, v34
	v_bfe_i32 v58, v46, 0, 1
	s_nop 0
	v_cndmask_b32_e32 v47, -1, v35, vcc
	ds_read_b128 v[50:53], v48
	ds_read_b128 v[42:45], v48 offset:16
	ds_read_b128 v[38:41], v48 offset:32
	ds_read_b128 v[34:37], v48 offset:48
	ds_read_b128 v[54:57], v48 offset:9248
	s_waitcnt lgkmcnt(4)
	v_ashrrev_i32_e32 v49, 31, v50
	v_or_b32_e32 v49, 0x80000000, v49
	v_bitop3_b32 v138, v58, v49, v50 bitop3:0x60
	v_bfe_i32 v50, v47, 0, 1
	s_waitcnt lgkmcnt(0)
	v_ashrrev_i32_e32 v49, 31, v54
	v_or_b32_e32 v49, 0x80000000, v49
	v_bitop3_b32 v98, v50, v49, v54 bitop3:0x60
	v_ashrrev_i32_e32 v49, 31, v51
	v_or_b32_e32 v49, 0x80000000, v49
	v_bfe_i32 v50, v46, 1, 1
	v_bitop3_b32 v140, v50, v49, v51 bitop3:0x60
	v_ashrrev_i32_e32 v51, 31, v52
	v_or_b32_e32 v51, 0x80000000, v51
	v_bfe_i32 v54, v46, 2, 1
	v_bitop3_b32 v139, v54, v51, v52 bitop3:0x60
	v_ashrrev_i32_e32 v51, 31, v56
	v_or_b32_e32 v51, 0x80000000, v51
	v_bfe_i32 v52, v47, 2, 1
	v_bitop3_b32 v99, v52, v51, v56 bitop3:0x60
	v_ashrrev_i32_e32 v51, 31, v53
	v_ashrrev_i32_e32 v49, 31, v55
	v_or_b32_e32 v51, 0x80000000, v51
	v_bfe_i32 v52, v46, 3, 1
	v_or_b32_e32 v49, 0x80000000, v49
	v_bfe_i32 v50, v47, 1, 1
	v_bitop3_b32 v141, v52, v51, v53 bitop3:0x60
	v_ashrrev_i32_e32 v51, 31, v57
	v_bitop3_b32 v107, v50, v49, v55 bitop3:0x60
	v_or_b32_e32 v51, 0x80000000, v51
	v_bfe_i32 v52, v47, 3, 1
	v_max_u32_e32 v50, v98, v107
	v_bitop3_b32 v108, v52, v51, v57 bitop3:0x60
	v_max3_u32 v54, v50, v99, v108
	ds_read_b128 v[50:53], v48 offset:9264
	v_ashrrev_i32_e32 v55, 31, v42
	v_or_b32_e32 v55, 0x80000000, v55
	v_bfe_i32 v56, v46, 4, 1
	v_bitop3_b32 v142, v56, v55, v42 bitop3:0x60
	s_waitcnt lgkmcnt(0)
	v_ashrrev_i32_e32 v42, 31, v50
	v_or_b32_e32 v42, 0x80000000, v42
	v_bfe_i32 v55, v47, 4, 1
	v_bitop3_b32 v109, v55, v42, v50 bitop3:0x60
	v_ashrrev_i32_e32 v42, 31, v43
	v_or_b32_e32 v42, 0x80000000, v42
	v_bfe_i32 v50, v46, 5, 1
	v_max_u32_e32 v49, v138, v140
	v_bitop3_b32 v146, v50, v42, v43 bitop3:0x60
	v_ashrrev_i32_e32 v42, 31, v51
	v_max3_u32 v49, v49, v139, v141
	v_or_b32_e32 v42, 0x80000000, v42
	v_bfe_i32 v43, v47, 5, 1
	v_bitop3_b32 v113, v43, v42, v51 bitop3:0x60
	v_max3_u32 v42, v49, v142, v146
	v_ashrrev_i32_e32 v49, 31, v44
	v_or_b32_e32 v49, 0x80000000, v49
	v_bfe_i32 v50, v46, 6, 1
	v_bitop3_b32 v143, v50, v49, v44 bitop3:0x60
	v_ashrrev_i32_e32 v44, 31, v52
	v_or_b32_e32 v44, 0x80000000, v44
	v_bfe_i32 v49, v47, 6, 1
	v_bitop3_b32 v110, v49, v44, v52 bitop3:0x60
	v_ashrrev_i32_e32 v44, 31, v45
	v_or_b32_e32 v44, 0x80000000, v44
	v_bfe_i32 v49, v46, 7, 1
	v_bitop3_b32 v147, v49, v44, v45 bitop3:0x60
	v_ashrrev_i32_e32 v44, 31, v53
	v_or_b32_e32 v44, 0x80000000, v44
	v_bfe_i32 v45, v47, 7, 1
	v_max3_u32 v43, v54, v109, v113
	v_bitop3_b32 v114, v45, v44, v53 bitop3:0x60
	v_max3_u32 v49, v42, v143, v147
	v_max3_u32 v50, v43, v110, v114
	ds_read_b128 v[42:45], v48 offset:9280
	v_ashrrev_i32_e32 v51, 31, v38
	v_or_b32_e32 v51, 0x80000000, v51
	v_bfe_i32 v52, v46, 8, 1
	v_bitop3_b32 v144, v52, v51, v38 bitop3:0x60
	s_waitcnt lgkmcnt(0)
	v_ashrrev_i32_e32 v38, 31, v42
	v_or_b32_e32 v38, 0x80000000, v38
	v_bfe_i32 v51, v47, 8, 1
	v_bitop3_b32 v111, v51, v38, v42 bitop3:0x60
	v_ashrrev_i32_e32 v38, 31, v39
	v_or_b32_e32 v38, 0x80000000, v38
	v_bfe_i32 v42, v46, 9, 1
	v_bitop3_b32 v148, v42, v38, v39 bitop3:0x60
	v_ashrrev_i32_e32 v38, 31, v43
	v_or_b32_e32 v38, 0x80000000, v38
	v_bfe_i32 v39, v47, 9, 1
	v_ashrrev_i32_e32 v42, 31, v40
	v_bitop3_b32 v115, v39, v38, v43 bitop3:0x60
	v_or_b32_e32 v42, 0x80000000, v42
	v_bfe_i32 v43, v46, 10, 1
	v_bitop3_b32 v145, v43, v42, v40 bitop3:0x60
	v_ashrrev_i32_e32 v40, 31, v44
	v_or_b32_e32 v40, 0x80000000, v40
	v_bfe_i32 v42, v47, 10, 1
	v_bitop3_b32 v112, v42, v40, v44 bitop3:0x60
	v_ashrrev_i32_e32 v40, 31, v41
	v_or_b32_e32 v40, 0x80000000, v40
	v_bfe_i32 v42, v46, 11, 1
	v_bitop3_b32 v149, v42, v40, v41 bitop3:0x60
	v_ashrrev_i32_e32 v40, 31, v45
	v_or_b32_e32 v40, 0x80000000, v40
	v_bfe_i32 v41, v47, 11, 1
	v_max3_u32 v38, v49, v144, v148
	v_max3_u32 v39, v50, v111, v115
	v_bitop3_b32 v116, v41, v40, v45 bitop3:0x60
	v_max3_u32 v42, v38, v145, v149
	v_max3_u32 v43, v39, v112, v116
	ds_read_b128 v[38:41], v48 offset:9296
	v_ashrrev_i32_e32 v44, 31, v34
	v_or_b32_e32 v44, 0x80000000, v44
	v_bfe_i32 v45, v46, 12, 1
	v_bitop3_b32 v150, v45, v44, v34 bitop3:0x60
	s_waitcnt lgkmcnt(0)
	v_ashrrev_i32_e32 v34, 31, v38
	v_or_b32_e32 v34, 0x80000000, v34
	v_bfe_i32 v44, v47, 12, 1
	v_bitop3_b32 v117, v44, v34, v38 bitop3:0x60
	v_ashrrev_i32_e32 v34, 31, v35
	v_or_b32_e32 v34, 0x80000000, v34
	v_bfe_i32 v38, v46, 13, 1
	v_bitop3_b32 v152, v38, v34, v35 bitop3:0x60
	v_ashrrev_i32_e32 v34, 31, v39
	v_or_b32_e32 v34, 0x80000000, v34
	v_bfe_i32 v35, v47, 13, 1
	v_ashrrev_i32_e32 v38, 31, v36
	v_bitop3_b32 v119, v35, v34, v39 bitop3:0x60
	v_or_b32_e32 v38, 0x80000000, v38
	v_bfe_i32 v39, v46, 14, 1
	v_bitop3_b32 v151, v39, v38, v36 bitop3:0x60
	v_ashrrev_i32_e32 v36, 31, v40
	v_or_b32_e32 v36, 0x80000000, v36
	v_bfe_i32 v38, v47, 14, 1
	v_bitop3_b32 v118, v38, v36, v40 bitop3:0x60
	v_ashrrev_i32_e32 v36, 31, v37
	v_or_b32_e32 v36, 0x80000000, v36
	v_bfe_i32 v38, v46, 15, 1
	v_bitop3_b32 v154, v38, v36, v37 bitop3:0x60
	v_ashrrev_i32_e32 v36, 31, v41
	v_or_b32_e32 v36, 0x80000000, v36
	v_bfe_i32 v37, v47, 15, 1
	v_max3_u32 v34, v42, v150, v152
	v_max3_u32 v35, v43, v117, v119
	v_bitop3_b32 v121, v37, v36, v41 bitop3:0x60
	v_max3_u32 v42, v34, v151, v154
	v_max3_u32 v43, v35, v118, v121
	ds_read_b128 v[34:37], v48 offset:64
	ds_read_b128 v[38:41], v48 offset:9312
	v_bfe_i32 v45, v46, 16, 1
	s_waitcnt lgkmcnt(1)
; #define LAS __attribute__((address_space(3)))
; __device__ __forceinline__ void select_phase(const bf16_t* Z, const bf16_t* KIb, unsigned* MASKb, unsigned* itemcnt, LAS unsigned char* lds, int wave_in, int lane_in, int bid, int G, int sub) {
;     ...
; #pragma unroll
;                 for (int e4 = 0; e4 < 8; ++e4) {
;                     const f32x4 va = *(const LAS f32x4*)(srow + 4 * e4), vb = *(const LAS f32x4*)(srow + SCS + 4 * e4);
; #pragma unroll
;                     for (int e = 0; e < 4; ++e) {
;                         const int ii = c * 32 + e4 * 4 + e;
;                         const unsigned ba = __float_as_uint(va[e]), bb = __float_as_uint(vb[e]);
;                         ua[ii] = (ba ^ ((unsigned)((int)ba >> 31) | 0x80000000u)) & (unsigned)__builtin_amdgcn_sbfe(adma, e4 * 4 + e, 1);
;                         ub[ii] = (bb ^ ((unsigned)((int)bb >> 31) | 0x80000000u)) & (unsigned)__builtin_amdgcn_sbfe(admb, e4 * 4 + e, 1);
;                         vmaxa = max(vmaxa, ua[ii]); vmaxb = max(vmaxb, ub[ii]);
;                     }
;                 }
	v_ashrrev_i32_e32 v44, 31, v34
	v_or_b32_e32 v44, 0x80000000, v44
	v_bitop3_b32 v153, v45, v44, v34 bitop3:0x60
	s_waitcnt lgkmcnt(0)
	v_ashrrev_i32_e32 v34, 31, v38
	v_or_b32_e32 v34, 0x80000000, v34
	v_bfe_i32 v44, v47, 16, 1
	v_bitop3_b32 v120, v44, v34, v38 bitop3:0x60
	v_ashrrev_i32_e32 v34, 31, v35
	v_or_b32_e32 v34, 0x80000000, v34
	v_bfe_i32 v38, v46, 17, 1
	v_bitop3_b32 v156, v38, v34, v35 bitop3:0x60
	v_ashrrev_i32_e32 v34, 31, v39
	v_or_b32_e32 v34, 0x80000000, v34
	v_bfe_i32 v35, v47, 17, 1
	v_ashrrev_i32_e32 v38, 31, v36
	v_bitop3_b32 v123, v35, v34, v39 bitop3:0x60
	v_or_b32_e32 v38, 0x80000000, v38
	v_bfe_i32 v39, v46, 18, 1
	v_bitop3_b32 v155, v39, v38, v36 bitop3:0x60
	v_ashrrev_i32_e32 v36, 31, v40
	v_or_b32_e32 v36, 0x80000000, v36
	v_bfe_i32 v38, v47, 18, 1
	v_bitop3_b32 v122, v38, v36, v40 bitop3:0x60
	v_ashrrev_i32_e32 v36, 31, v37
	v_or_b32_e32 v36, 0x80000000, v36
	v_bfe_i32 v38, v46, 19, 1
	v_bitop3_b32 v157, v38, v36, v37 bitop3:0x60
	v_ashrrev_i32_e32 v36, 31, v41
	v_or_b32_e32 v36, 0x80000000, v36
	v_bfe_i32 v37, v47, 19, 1
	v_max3_u32 v34, v42, v153, v156
	v_max3_u32 v35, v43, v120, v123
	v_bitop3_b32 v124, v37, v36, v41 bitop3:0x60
	v_max3_u32 v42, v34, v155, v157
	v_max3_u32 v43, v35, v122, v124
	ds_read_b128 v[34:37], v48 offset:80
	ds_read_b128 v[38:41], v48 offset:9328
	v_bfe_i32 v45, v46, 20, 1
	s_waitcnt lgkmcnt(1)
	v_ashrrev_i32_e32 v44, 31, v34
	v_or_b32_e32 v44, 0x80000000, v44
	v_bitop3_b32 v158, v45, v44, v34 bitop3:0x60
	s_waitcnt lgkmcnt(0)
	v_ashrrev_i32_e32 v34, 31, v38
	v_or_b32_e32 v34, 0x80000000, v34
	v_bfe_i32 v44, v47, 20, 1
	v_bitop3_b32 v125, v44, v34, v38 bitop3:0x60
	v_ashrrev_i32_e32 v34, 31, v35
	v_or_b32_e32 v34, 0x80000000, v34
	v_bfe_i32 v38, v46, 21, 1
	v_bitop3_b32 v160, v38, v34, v35 bitop3:0x60
	v_ashrrev_i32_e32 v34, 31, v39
	v_or_b32_e32 v34, 0x80000000, v34
	v_bfe_i32 v35, v47, 21, 1
	v_ashrrev_i32_e32 v38, 31, v36
	v_bitop3_b32 v127, v35, v34, v39 bitop3:0x60
	v_or_b32_e32 v38, 0x80000000, v38
	v_bfe_i32 v39, v46, 22, 1
	v_bitop3_b32 v159, v39, v38, v36 bitop3:0x60
	v_ashrrev_i32_e32 v36, 31, v40
	v_or_b32_e32 v36, 0x80000000, v36
	v_bfe_i32 v38, v47, 22, 1
	v_bitop3_b32 v126, v38, v36, v40 bitop3:0x60
	v_ashrrev_i32_e32 v36, 31, v37
	v_or_b32_e32 v36, 0x80000000, v36
	v_bfe_i32 v38, v46, 23, 1
	v_bitop3_b32 v161, v38, v36, v37 bitop3:0x60
	v_ashrrev_i32_e32 v36, 31, v41
	v_or_b32_e32 v36, 0x80000000, v36
	v_bfe_i32 v37, v47, 23, 1
	v_max3_u32 v34, v42, v158, v160
	v_max3_u32 v35, v43, v125, v127
	v_bitop3_b32 v128, v37, v36, v41 bitop3:0x60
	v_max3_u32 v42, v34, v159, v161
	v_max3_u32 v43, v35, v126, v128
	ds_read_b128 v[34:37], v48 offset:96
	ds_read_b128 v[38:41], v48 offset:9344
	v_bfe_i32 v45, v46, 24, 1
	s_waitcnt lgkmcnt(1)
	v_ashrrev_i32_e32 v44, 31, v34
	v_or_b32_e32 v44, 0x80000000, v44
	v_bitop3_b32 v167, v45, v44, v34 bitop3:0x60
	s_waitcnt lgkmcnt(0)
	v_ashrrev_i32_e32 v34, 31, v38
	v_or_b32_e32 v34, 0x80000000, v34
	v_bfe_i32 v44, v47, 24, 1
	v_bitop3_b32 v129, v44, v34, v38 bitop3:0x60
	v_ashrrev_i32_e32 v34, 31, v35
	v_or_b32_e32 v34, 0x80000000, v34
	v_bfe_i32 v38, v46, 25, 1
	v_bitop3_b32 v169, v38, v34, v35 bitop3:0x60
	v_ashrrev_i32_e32 v34, 31, v39
	v_or_b32_e32 v34, 0x80000000, v34
	v_bfe_i32 v35, v47, 25, 1
	v_ashrrev_i32_e32 v38, 31, v36
	v_bitop3_b32 v131, v35, v34, v39 bitop3:0x60
	v_or_b32_e32 v38, 0x80000000, v38
	v_bfe_i32 v39, v46, 26, 1
	v_bitop3_b32 v168, v39, v38, v36 bitop3:0x60
	v_ashrrev_i32_e32 v36, 31, v40
	v_or_b32_e32 v36, 0x80000000, v36
	v_bfe_i32 v38, v47, 26, 1
	v_bitop3_b32 v130, v38, v36, v40 bitop3:0x60
	v_ashrrev_i32_e32 v36, 31, v37
	v_or_b32_e32 v36, 0x80000000, v36
	v_bfe_i32 v38, v46, 27, 1
	v_bitop3_b32 v170, v38, v36, v37 bitop3:0x60
	v_ashrrev_i32_e32 v36, 31, v41
	v_or_b32_e32 v36, 0x80000000, v36
	v_bfe_i32 v37, v47, 27, 1
	v_max3_u32 v34, v42, v167, v169
	v_max3_u32 v35, v43, v129, v131
	v_bitop3_b32 v132, v37, v36, v41 bitop3:0x60
	v_max3_u32 v42, v34, v168, v170
	v_max3_u32 v43, v35, v130, v132
	ds_read_b128 v[34:37], v48 offset:112
	ds_read_b128 v[38:41], v48 offset:9360
	v_bfe_i32 v45, v46, 28, 1
	s_waitcnt lgkmcnt(0)
	s_waitcnt lgkmcnt(0)
	v_ashrrev_i32_e32 v44, 31, v34
	v_or_b32_e32 v44, 0x80000000, v44
	v_bitop3_b32 v173, v45, v44, v34 bitop3:0x60
	v_ashrrev_i32_e32 v34, 31, v38
	v_or_b32_e32 v34, 0x80000000, v34
	v_bfe_i32 v44, v47, 28, 1
	v_bitop3_b32 v133, v44, v34, v38 bitop3:0x60
	v_ashrrev_i32_e32 v34, 31, v35
	v_or_b32_e32 v34, 0x80000000, v34
	v_bfe_i32 v38, v46, 29, 1
	v_bitop3_b32 v174, v38, v34, v35 bitop3:0x60
	v_ashrrev_i32_e32 v34, 31, v39
	v_or_b32_e32 v34, 0x80000000, v34
	v_bfe_i32 v35, v47, 29, 1
	v_ashrrev_i32_e32 v38, 31, v36
	v_bitop3_b32 v134, v35, v34, v39 bitop3:0x60
	v_or_b32_e32 v38, 0x80000000, v38
	v_bfe_i32 v39, v46, 30, 1
	v_bitop3_b32 v175, v39, v38, v36 bitop3:0x60
	v_ashrrev_i32_e32 v36, 31, v40
	v_or_b32_e32 v36, 0x80000000, v36
	v_bfe_i32 v38, v47, 30, 1
	v_bitop3_b32 v136, v38, v36, v40 bitop3:0x60
	v_ashrrev_i32_e32 v36, 31, v37
	v_or_b32_e32 v36, 0x80000000, v36
	v_ashrrev_i32_e32 v38, 31, v46
	v_bitop3_b32 v176, v38, v36, v37 bitop3:0x60
	v_ashrrev_i32_e32 v36, 31, v41
	v_or_b32_e32 v36, 0x80000000, v36
	v_ashrrev_i32_e32 v37, 31, v47
	v_max3_u32 v34, v42, v173, v174
	v_max3_u32 v35, v43, v133, v134
	v_bitop3_b32 v137, v37, v36, v41 bitop3:0x60
	v_max3_u32 v185, v34, v175, v176
	v_max3_u32 v177, v35, v136, v137
	s_branch .Lcv_join
; #define LAS __attribute__((address_space(3)))
; __device__ __forceinline__ void select_phase(const bf16_t* Z, const bf16_t* KIb, unsigned* MASKb, unsigned* itemcnt, LAS unsigned char* lds, int wave_in, int lane_in, int bid, int G, int sub) {
;     ...
;                 const LAS float* srow = sc + (2 * wave) * SCS + 36 * lane;
;                 const int ema = qa - 2048 * c - 32 * lane, emb = ema + 1;
;                 const int adma = (int)(ema >= 31 ? 0xffffffffu : ema < 0 ? 0u : ((2u << ema) - 1u)), admb = (int)(emb >= 31 ? 0xffffffffu : emb < 0 ? 0u : ((2u << emb) - 1u));
; #pragma unroll
;                 for (int e4 = 0; e4 < 8; ++e4) {
;                     const f32x4 va = *(const LAS f32x4*)(srow + 4 * e4), vb = *(const LAS f32x4*)(srow + SCS + 4 * e4);
; #pragma unroll
;                     for (int e = 0; e < 4; ++e) {
;                         const int ii = c * 32 + e4 * 4 + e;
;                         const unsigned ba = __float_as_uint(va[e]), bb = __float_as_uint(vb[e]);
;                         ua[ii] = (ba ^ ((unsigned)((int)ba >> 31) | 0x80000000u)) & (unsigned)__builtin_amdgcn_sbfe(adma, e4 * 4 + e, 1);
;                         ub[ii] = (bb ^ ((unsigned)((int)bb >> 31) | 0x80000000u)) & (unsigned)__builtin_amdgcn_sbfe(admb, e4 * 4 + e, 1);
;                         vmaxa = max(vmaxa, ua[ii]); vmaxb = max(vmaxb, ub[ii]);
;                     }
;                 }
.Lcv_fast:
	v_sub_u32_e32 v34, s75, v172
	v_lshlrev_b32_e64 v35, v34, 2
	v_cmp_gt_i32_e32 vcc, 0, v34
	v_add_u32_e32 v35, -1, v35
	v_cmp_gt_i32_e64 s[4:5], 31, v34
	v_cndmask_b32_e64 v35, v35, 0, vcc
	v_add_u32_e32 v48, s9, v0
	v_cndmask_b32_e64 v46, -1, v35, s[4:5]
	v_lshlrev_b32_e64 v35, v34, 4
	v_add_u32_e32 v35, -1, v35
	v_cndmask_b32_e64 v35, v35, 0, vcc
	v_cmp_gt_i32_e32 vcc, 30, v34
	s_nop 0
	v_cndmask_b32_e32 v47, -1, v35, vcc
	ds_read_b128 v[50:53], v48
	ds_read_b128 v[42:45], v48 offset:16
	ds_read_b128 v[38:41], v48 offset:32
	ds_read_b128 v[34:37], v48 offset:48
	ds_read_b128 v[54:57], v48 offset:9248
	s_waitcnt lgkmcnt(4)
	v_ashrrev_i32_e32 v49, 31, v50
	v_or_b32_e32 v49, 0x80000000, v49
	v_xor_b32_e32 v138, v49, v50
	s_waitcnt lgkmcnt(0)
	v_ashrrev_i32_e32 v49, 31, v54
	v_or_b32_e32 v49, 0x80000000, v49
	v_xor_b32_e32 v98, v49, v54
	v_ashrrev_i32_e32 v49, 31, v51
	v_or_b32_e32 v49, 0x80000000, v49
	v_xor_b32_e32 v140, v49, v51
	v_ashrrev_i32_e32 v51, 31, v52
	v_or_b32_e32 v51, 0x80000000, v51
	v_xor_b32_e32 v139, v51, v52
	v_ashrrev_i32_e32 v51, 31, v56
	v_or_b32_e32 v51, 0x80000000, v51
	v_xor_b32_e32 v99, v51, v56
	v_ashrrev_i32_e32 v51, 31, v53
	v_ashrrev_i32_e32 v49, 31, v55
	v_or_b32_e32 v51, 0x80000000, v51
	v_or_b32_e32 v49, 0x80000000, v49
	v_xor_b32_e32 v141, v51, v53
	v_ashrrev_i32_e32 v51, 31, v57
	v_xor_b32_e32 v107, v49, v55
	v_or_b32_e32 v51, 0x80000000, v51
	v_max_u32_e32 v50, v98, v107
	v_xor_b32_e32 v108, v51, v57
	v_max3_u32 v54, v50, v99, v108
	ds_read_b128 v[50:53], v48 offset:9264
	v_ashrrev_i32_e32 v55, 31, v42
	v_or_b32_e32 v55, 0x80000000, v55
	v_xor_b32_e32 v142, v55, v42
	s_waitcnt lgkmcnt(0)
	v_ashrrev_i32_e32 v42, 31, v50
	v_or_b32_e32 v42, 0x80000000, v42
	v_xor_b32_e32 v109, v42, v50
	v_ashrrev_i32_e32 v42, 31, v43
	v_or_b32_e32 v42, 0x80000000, v42
	v_max_u32_e32 v49, v138, v140
	v_xor_b32_e32 v146, v42, v43
	v_ashrrev_i32_e32 v42, 31, v51
	v_max3_u32 v49, v49, v139, v141
	v_or_b32_e32 v42, 0x80000000, v42
	v_xor_b32_e32 v113, v42, v51
	v_max3_u32 v42, v49, v142, v146
	v_ashrrev_i32_e32 v49, 31, v44
	v_or_b32_e32 v49, 0x80000000, v49
	v_xor_b32_e32 v143, v49, v44
	v_ashrrev_i32_e32 v44, 31, v52
	v_or_b32_e32 v44, 0x80000000, v44
	v_xor_b32_e32 v110, v44, v52
	v_ashrrev_i32_e32 v44, 31, v45
	v_or_b32_e32 v44, 0x80000000, v44
	v_xor_b32_e32 v147, v44, v45
	v_ashrrev_i32_e32 v44, 31, v53
	v_or_b32_e32 v44, 0x80000000, v44
	v_max3_u32 v43, v54, v109, v113
	v_xor_b32_e32 v114, v44, v53
	v_max3_u32 v49, v42, v143, v147
	v_max3_u32 v50, v43, v110, v114
	ds_read_b128 v[42:45], v48 offset:9280
	v_ashrrev_i32_e32 v51, 31, v38
	v_or_b32_e32 v51, 0x80000000, v51
	v_xor_b32_e32 v144, v51, v38
	s_waitcnt lgkmcnt(0)
	v_ashrrev_i32_e32 v38, 31, v42
	v_or_b32_e32 v38, 0x80000000, v38
	v_xor_b32_e32 v111, v38, v42
	v_ashrrev_i32_e32 v38, 31, v39
	v_or_b32_e32 v38, 0x80000000, v38
	v_xor_b32_e32 v148, v38, v39
	v_ashrrev_i32_e32 v38, 31, v43
	v_or_b32_e32 v38, 0x80000000, v38
	v_ashrrev_i32_e32 v42, 31, v40
	v_xor_b32_e32 v115, v38, v43
	v_or_b32_e32 v42, 0x80000000, v42
	v_xor_b32_e32 v145, v42, v40
	v_ashrrev_i32_e32 v40, 31, v44
	v_or_b32_e32 v40, 0x80000000, v40
	v_xor_b32_e32 v112, v40, v44
	v_ashrrev_i32_e32 v40, 31, v41
	v_or_b32_e32 v40, 0x80000000, v40
	v_xor_b32_e32 v149, v40, v41
	v_ashrrev_i32_e32 v40, 31, v45
	v_or_b32_e32 v40, 0x80000000, v40
	v_max3_u32 v38, v49, v144, v148
	v_max3_u32 v39, v50, v111, v115
	v_xor_b32_e32 v116, v40, v45
	v_max3_u32 v42, v38, v145, v149
	v_max3_u32 v43, v39, v112, v116
	ds_read_b128 v[38:41], v48 offset:9296
	v_ashrrev_i32_e32 v44, 31, v34
	v_or_b32_e32 v44, 0x80000000, v44
	v_xor_b32_e32 v150, v44, v34
	s_waitcnt lgkmcnt(0)
	v_ashrrev_i32_e32 v34, 31, v38
	v_or_b32_e32 v34, 0x80000000, v34
	v_xor_b32_e32 v117, v34, v38
	v_ashrrev_i32_e32 v34, 31, v35
	v_or_b32_e32 v34, 0x80000000, v34
	v_xor_b32_e32 v152, v34, v35
	v_ashrrev_i32_e32 v34, 31, v39
	v_or_b32_e32 v34, 0x80000000, v34
	v_ashrrev_i32_e32 v38, 31, v36
	v_xor_b32_e32 v119, v34, v39
	v_or_b32_e32 v38, 0x80000000, v38
	v_xor_b32_e32 v151, v38, v36
	v_ashrrev_i32_e32 v36, 31, v40
	v_or_b32_e32 v36, 0x80000000, v36
	v_xor_b32_e32 v118, v36, v40
	v_ashrrev_i32_e32 v36, 31, v37
	v_or_b32_e32 v36, 0x80000000, v36
	v_xor_b32_e32 v154, v36, v37
	v_ashrrev_i32_e32 v36, 31, v41
	v_or_b32_e32 v36, 0x80000000, v36
	v_max3_u32 v34, v42, v150, v152
	v_max3_u32 v35, v43, v117, v119
	v_xor_b32_e32 v121, v36, v41
	v_max3_u32 v42, v34, v151, v154
	v_max3_u32 v43, v35, v118, v121
	ds_read_b128 v[34:37], v48 offset:64
	ds_read_b128 v[38:41], v48 offset:9312
	s_waitcnt lgkmcnt(1)
; #define LAS __attribute__((address_space(3)))
; __device__ __forceinline__ void select_phase(const bf16_t* Z, const bf16_t* KIb, unsigned* MASKb, unsigned* itemcnt, LAS unsigned char* lds, int wave_in, int lane_in, int bid, int G, int sub) {
;     ...
; #pragma unroll
;                 for (int e4 = 0; e4 < 8; ++e4) {
;                     const f32x4 va = *(const LAS f32x4*)(srow + 4 * e4), vb = *(const LAS f32x4*)(srow + SCS + 4 * e4);
; #pragma unroll
;                     for (int e = 0; e < 4; ++e) {
;                         const int ii = c * 32 + e4 * 4 + e;
;                         const unsigned ba = __float_as_uint(va[e]), bb = __float_as_uint(vb[e]);
;                         ua[ii] = (ba ^ ((unsigned)((int)ba >> 31) | 0x80000000u)) & (unsigned)__builtin_amdgcn_sbfe(adma, e4 * 4 + e, 1);
;                         ub[ii] = (bb ^ ((unsigned)((int)bb >> 31) | 0x80000000u)) & (unsigned)__builtin_amdgcn_sbfe(admb, e4 * 4 + e, 1);
;                         vmaxa = max(vmaxa, ua[ii]); vmaxb = max(vmaxb, ub[ii]);
;                     }
;                 }
;                 asm volatile("s_waitcnt lgkmcnt(0)" ::: "memory");
;                 __syncthreads();
	v_ashrrev_i32_e32 v44, 31, v34
	v_or_b32_e32 v44, 0x80000000, v44
	v_xor_b32_e32 v153, v44, v34
	s_waitcnt lgkmcnt(0)
	v_ashrrev_i32_e32 v34, 31, v38
	v_or_b32_e32 v34, 0x80000000, v34
	v_xor_b32_e32 v120, v34, v38
	v_ashrrev_i32_e32 v34, 31, v35
	v_or_b32_e32 v34, 0x80000000, v34
	v_xor_b32_e32 v156, v34, v35
	v_ashrrev_i32_e32 v34, 31, v39
	v_or_b32_e32 v34, 0x80000000, v34
	v_ashrrev_i32_e32 v38, 31, v36
	v_xor_b32_e32 v123, v34, v39
	v_or_b32_e32 v38, 0x80000000, v38
	v_xor_b32_e32 v155, v38, v36
	v_ashrrev_i32_e32 v36, 31, v40
	v_or_b32_e32 v36, 0x80000000, v36
	v_xor_b32_e32 v122, v36, v40
	v_ashrrev_i32_e32 v36, 31, v37
	v_or_b32_e32 v36, 0x80000000, v36
	v_xor_b32_e32 v157, v36, v37
	v_ashrrev_i32_e32 v36, 31, v41
	v_or_b32_e32 v36, 0x80000000, v36
	v_max3_u32 v34, v42, v153, v156
	v_max3_u32 v35, v43, v120, v123
	v_xor_b32_e32 v124, v36, v41
	v_max3_u32 v42, v34, v155, v157
	v_max3_u32 v43, v35, v122, v124
	ds_read_b128 v[34:37], v48 offset:80
	ds_read_b128 v[38:41], v48 offset:9328
	s_waitcnt lgkmcnt(1)
	v_ashrrev_i32_e32 v44, 31, v34
	v_or_b32_e32 v44, 0x80000000, v44
	v_xor_b32_e32 v158, v44, v34
	s_waitcnt lgkmcnt(0)
	v_ashrrev_i32_e32 v34, 31, v38
	v_or_b32_e32 v34, 0x80000000, v34
	v_xor_b32_e32 v125, v34, v38
	v_ashrrev_i32_e32 v34, 31, v35
	v_or_b32_e32 v34, 0x80000000, v34
	v_xor_b32_e32 v160, v34, v35
	v_ashrrev_i32_e32 v34, 31, v39
	v_or_b32_e32 v34, 0x80000000, v34
	v_ashrrev_i32_e32 v38, 31, v36
	v_xor_b32_e32 v127, v34, v39
	v_or_b32_e32 v38, 0x80000000, v38
	v_xor_b32_e32 v159, v38, v36
	v_ashrrev_i32_e32 v36, 31, v40
	v_or_b32_e32 v36, 0x80000000, v36
	v_xor_b32_e32 v126, v36, v40
	v_ashrrev_i32_e32 v36, 31, v37
	v_or_b32_e32 v36, 0x80000000, v36
	v_xor_b32_e32 v161, v36, v37
	v_ashrrev_i32_e32 v36, 31, v41
	v_or_b32_e32 v36, 0x80000000, v36
	v_max3_u32 v34, v42, v158, v160
	v_max3_u32 v35, v43, v125, v127
	v_xor_b32_e32 v128, v36, v41
	v_max3_u32 v42, v34, v159, v161
	v_max3_u32 v43, v35, v126, v128
	ds_read_b128 v[34:37], v48 offset:96
	ds_read_b128 v[38:41], v48 offset:9344
	s_waitcnt lgkmcnt(1)
	v_ashrrev_i32_e32 v44, 31, v34
	v_or_b32_e32 v44, 0x80000000, v44
	v_xor_b32_e32 v167, v44, v34
	s_waitcnt lgkmcnt(0)
	v_ashrrev_i32_e32 v34, 31, v38
	v_or_b32_e32 v34, 0x80000000, v34
	v_xor_b32_e32 v129, v34, v38
	v_ashrrev_i32_e32 v34, 31, v35
	v_or_b32_e32 v34, 0x80000000, v34
	v_xor_b32_e32 v169, v34, v35
	v_ashrrev_i32_e32 v34, 31, v39
	v_or_b32_e32 v34, 0x80000000, v34
	v_ashrrev_i32_e32 v38, 31, v36
	v_xor_b32_e32 v131, v34, v39
	v_or_b32_e32 v38, 0x80000000, v38
	v_xor_b32_e32 v168, v38, v36
	v_ashrrev_i32_e32 v36, 31, v40
	v_or_b32_e32 v36, 0x80000000, v36
	v_xor_b32_e32 v130, v36, v40
	v_ashrrev_i32_e32 v36, 31, v37
	v_or_b32_e32 v36, 0x80000000, v36
	v_xor_b32_e32 v170, v36, v37
	v_ashrrev_i32_e32 v36, 31, v41
	v_or_b32_e32 v36, 0x80000000, v36
	v_max3_u32 v34, v42, v167, v169
	v_max3_u32 v35, v43, v129, v131
	v_xor_b32_e32 v132, v36, v41
	v_max3_u32 v42, v34, v168, v170
	v_max3_u32 v43, v35, v130, v132
	ds_read_b128 v[34:37], v48 offset:112
	ds_read_b128 v[38:41], v48 offset:9360
	s_waitcnt lgkmcnt(0)
	s_waitcnt lgkmcnt(0)
	v_ashrrev_i32_e32 v44, 31, v34
	v_or_b32_e32 v44, 0x80000000, v44
	v_xor_b32_e32 v173, v44, v34
	v_ashrrev_i32_e32 v34, 31, v38
	v_or_b32_e32 v34, 0x80000000, v34
	v_xor_b32_e32 v133, v34, v38
	v_ashrrev_i32_e32 v34, 31, v35
	v_or_b32_e32 v34, 0x80000000, v34
	v_xor_b32_e32 v174, v34, v35
	v_ashrrev_i32_e32 v34, 31, v39
	v_or_b32_e32 v34, 0x80000000, v34
	v_ashrrev_i32_e32 v38, 31, v36
	v_xor_b32_e32 v134, v34, v39
	v_or_b32_e32 v38, 0x80000000, v38
	v_xor_b32_e32 v175, v38, v36
	v_ashrrev_i32_e32 v36, 31, v40
	v_or_b32_e32 v36, 0x80000000, v36
	v_xor_b32_e32 v136, v36, v40
	v_ashrrev_i32_e32 v36, 31, v37
	v_or_b32_e32 v36, 0x80000000, v36
	v_xor_b32_e32 v176, v36, v37
	v_ashrrev_i32_e32 v36, 31, v41
	v_or_b32_e32 v36, 0x80000000, v36
	v_max3_u32 v34, v42, v173, v174
	v_max3_u32 v35, v43, v133, v134
	v_xor_b32_e32 v137, v36, v41
	v_max3_u32 v185, v34, v175, v176
	v_max3_u32 v177, v35, v136, v137
.Lcv_join:
	s_barrier
	s_cmp_lt_i32 s10, 2
	v_mov_b32_e32 v46, 0
	s_cbranch_scc1 .LBB0_129
